# phase-9 cross-attention units remapped so each XCD runs the 16 query blocks of two (batch, head) pairs: a K/V block is fetched into one XCD's L2 instead of all eight
# baseline (speedup 1.0000x reference)
; __device__ __forceinline__ float sigm(float x) { return 1.f / (1.f + __expf(-x)); }
; __device__ __forceinline__ u32x4 pack8(const float (&f)[8]) { u32x4 w; w.x = pk2(f[0], f[1]); w.y = pk2(f[2], f[3]); w.z = pk2(f[4], f[5]); w.w = pk2(f[6], f[7]); return w; }
; __device__ __forceinline__ void ffn_conv_item(int tid_in, int b, int strip, bf16_t* h1, const bf16_t* h2, const float* cw, const float* cb, bool st = true) {
;     ...
;         for (int j = 0; j < 4; ++j) {
;             const size_t off = off0 + (size_t)(32 * blk + 8 * j + rl) * 5632;
;             const u32x4 cgv = cg4[j], cvv = cv4[j];
;             float xg[8], xv[8], yg[8], yv[8]; unpack8(cgv, xg); unpack8(cvv, xv);
; #pragma unroll
;             for (int e = 0; e < 8; ++e) { yg[e] = bg[e] + wg[2][e] * xg[e]; yv[e] = bv[e] + wv[2][e] * xv[e]; }
; #pragma unroll
;             for (int d = 1; d <= 2; ++d) {
;                 const bool own = (rl + d <= 7); const int src = (lane + 64 - 8 * d) & 63;
;                 const u32x4 sg = own ? cgv : pg, sv = own ? cvv : pv;
;                 u32x4 g, v; g.x = __shfl(sg.x, src); g.y = __shfl(sg.y, src); g.z = __shfl(sg.z, src); g.w = __shfl(sg.w, src);
;                 v.x = __shfl(sv.x, src); v.y = __shfl(sv.y, src); v.z = __shfl(sv.z, src); v.w = __shfl(sv.w, src);
;                 float dg[8], dv[8]; unpack8(g, dg); unpack8(v, dv);
; #pragma unroll
;                 for (int e = 0; e < 8; ++e) { yg[e] += wg[2 - d][e] * dg[e]; yv[e] += wv[2 - d][e] * dv[e]; }
;             }
; #pragma unroll
;             for (int e = 0; e < 8; ++e) yg[e] = yg[e] * sigm(yg[e]) * yv[e];
;             { const u32x4 o_ = pack8(yg); if (st) *(u32x4*)(h1 + off) = o_; else asm volatile("" :: "v"(o_)); }
;             pg = cgv; pv = cvv;
;         }
; #pragma unroll
;         for (int j = 0; j < 4; ++j) { cg4[j] = ng4[j]; cv4[j] = nv4[j]; }
;     }
.Lcv_join7:
	s_add_i32 s9, s9, 1
	s_waitcnt lgkmcnt(2)
	v_lshlrev_b32_e32 v114, 16, v106
	v_and_b32_e32 v115, 0xffff0000, v106
	v_lshlrev_b32_e32 v116, 16, v107
	v_and_b32_e32 v117, 0xffff0000, v107
	v_lshlrev_b32_e32 v118, 16, v108
	v_and_b32_e32 v119, 0xffff0000, v108
	v_lshlrev_b32_e32 v120, 16, v109
	v_and_b32_e32 v121, 0xffff0000, v109
	v_lshlrev_b32_e32 v122, 16, v110
	v_and_b32_e32 v123, 0xffff0000, v110
	v_lshlrev_b32_e32 v124, 16, v111
	v_and_b32_e32 v125, 0xffff0000, v111
	v_lshlrev_b32_e32 v126, 16, v112
	v_and_b32_e32 v127, 0xffff0000, v112
	v_lshlrev_b32_e32 v128, 16, v113
	v_and_b32_e32 v129, 0xffff0000, v113
	v_pk_fma_f32 v[130:131], v[34:35], v[114:115], v[66:67]
	v_pk_fma_f32 v[132:133], v[36:37], v[116:117], v[68:69]
	v_pk_fma_f32 v[134:135], v[38:39], v[118:119], v[70:71]
	v_pk_fma_f32 v[136:137], v[40:41], v[120:121], v[72:73]
	v_pk_fma_f32 v[138:139], v[42:43], v[122:123], v[74:75]
	v_pk_fma_f32 v[140:141], v[44:45], v[124:125], v[76:77]
	v_pk_fma_f32 v[142:143], v[46:47], v[126:127], v[78:79]
	v_pk_fma_f32 v[144:145], v[48:49], v[128:129], v[80:81]
	v_pk_fma_f32 v[66:67], v[18:19], v[114:115], v[82:83]
	v_pk_fma_f32 v[68:69], v[20:21], v[116:117], v[84:85]
	v_pk_fma_f32 v[70:71], v[22:23], v[118:119], v[86:87]
	v_pk_fma_f32 v[72:73], v[24:25], v[120:121], v[88:89]
	v_pk_fma_f32 v[74:75], v[26:27], v[122:123], v[90:91]
	v_pk_fma_f32 v[76:77], v[28:29], v[124:125], v[92:93]
	v_pk_fma_f32 v[78:79], v[30:31], v[126:127], v[94:95]
	v_pk_fma_f32 v[80:81], v[32:33], v[128:129], v[96:97]
	v_pk_fma_f32 v[82:83], v[2:3], v[114:115], v[50:51]
	v_pk_fma_f32 v[84:85], v[4:5], v[116:117], v[52:53]
	v_pk_fma_f32 v[86:87], v[6:7], v[118:119], v[54:55]
	v_pk_fma_f32 v[88:89], v[8:9], v[120:121], v[56:57]
	v_pk_fma_f32 v[90:91], v[10:11], v[122:123], v[58:59]
	v_pk_fma_f32 v[92:93], v[12:13], v[124:125], v[60:61]
	v_pk_fma_f32 v[94:95], v[14:15], v[126:127], v[62:63]
	v_pk_fma_f32 v[96:97], v[16:17], v[128:129], v[64:65]
	v_pk_mul_f32 v[148:149], v[130:131], s[34:35]
	v_pk_mul_f32 v[150:151], v[132:133], s[34:35]
	v_pk_mul_f32 v[152:153], v[134:135], s[34:35]
	v_pk_mul_f32 v[154:155], v[136:137], s[34:35]
	v_exp_f32_e32 v148, v148
	v_exp_f32_e32 v149, v149
	v_exp_f32_e32 v150, v150
	v_exp_f32_e32 v151, v151
	v_exp_f32_e32 v152, v152
	v_exp_f32_e32 v153, v153
	v_exp_f32_e32 v154, v154
	v_exp_f32_e32 v155, v155
	v_pk_add_f32 v[148:149], v[148:149], 1.0 op_sel_hi:[1,0]
	v_pk_add_f32 v[150:151], v[150:151], 1.0 op_sel_hi:[1,0]
	v_pk_add_f32 v[152:153], v[152:153], 1.0 op_sel_hi:[1,0]
	v_pk_add_f32 v[154:155], v[154:155], 1.0 op_sel_hi:[1,0]
	v_rcp_f32_e32 v148, v148
	v_rcp_f32_e32 v149, v149
	v_rcp_f32_e32 v150, v150
	v_rcp_f32_e32 v151, v151
	v_rcp_f32_e32 v152, v152
	v_rcp_f32_e32 v153, v153
	v_rcp_f32_e32 v154, v154
	v_rcp_f32_e32 v155, v155
	v_pk_mul_f32 v[130:131], v[130:131], v[148:149]
	v_pk_mul_f32 v[132:133], v[132:133], v[150:151]
	v_pk_mul_f32 v[134:135], v[134:135], v[152:153]
	v_pk_mul_f32 v[136:137], v[136:137], v[154:155]
	v_pk_mul_f32 v[130:131], v[130:131], v[138:139]
	v_pk_mul_f32 v[132:133], v[132:133], v[140:141]
	v_pk_mul_f32 v[134:135], v[134:135], v[142:143]
	v_pk_mul_f32 v[136:137], v[136:137], v[144:145]
	v_cvt_pk_bf16_f32 v148, v130, v131
	v_cvt_pk_bf16_f32 v149, v132, v133
	v_cvt_pk_bf16_f32 v150, v134, v135
	v_cvt_pk_bf16_f32 v151, v136, v137
	global_store_dwordx4 v159, v[148:151], s[40:41]
	s_add_u32 s40, s40, 0x2c00
	s_addc_u32 s41, s41, 0
	s_add_i32 s13, s13, 1
	s_cmp_lt_u32 s13, 8
	s_cbranch_scc1 .Lcv_loop
	s_branch .LBB0_17
	s_nop 0
	s_nop 0
	s_nop 0
	s_nop 0
	s_nop 0
	s_nop 0
	s_nop 0
	s_nop 0
	s_nop 0
	s_nop 0
	s_nop 0
	s_nop 0
	s_nop 0
	s_nop 0
	s_nop 0
	s_nop 0
	s_nop 0
	s_nop 0
	s_nop 0
	s_nop 0
	s_nop 0
	s_nop 0
	s_nop 0
	s_nop 0
	s_nop 0
	s_nop 0
	s_nop 0
	s_nop 0
	s_nop 0
	s_nop 0
	s_nop 0
	s_nop 0
	s_nop 0
	s_nop 0
	s_nop 0
	s_nop 0
	s_nop 0
	s_nop 0
	s_nop 0
	s_nop 0
	s_nop 0
	s_nop 0
	s_nop 0
	s_nop 0
	s_nop 0
	s_nop 0
	s_nop 0
	s_nop 0
	s_nop 0
	s_nop 0
	s_nop 0
	s_nop 0
	s_nop 0
	s_nop 0
	s_nop 0
	s_nop 0
	s_nop 0
	s_nop 0
	s_nop 0
	s_nop 0
	s_nop 0
	s_nop 0
	s_nop 0
	s_nop 0
	s_nop 0
	s_nop 0
	s_nop 0
	s_nop 0
	s_nop 0
	s_nop 0
	s_nop 0
	s_nop 0
	s_nop 0
	s_nop 0
	s_nop 0
	s_nop 0
	s_nop 0
	s_nop 0
	s_nop 0
	s_nop 0
	s_nop 0
	s_nop 0
	s_nop 0
	s_nop 0
	s_nop 0
	s_nop 0
	s_nop 0
	s_nop 0
	s_nop 0
	s_nop 0
	s_nop 0
	s_nop 0
	s_nop 0
	s_nop 0
	s_nop 0
	s_nop 0
	s_nop 0
	s_nop 0
	s_nop 0
	s_nop 0
	s_nop 0
	s_nop 0
	s_nop 0
	s_nop 0
	s_nop 0
	s_nop 0
	s_nop 0
	s_nop 0
	s_nop 0
	s_nop 0
	s_nop 0
	s_nop 0
	s_nop 0
	s_nop 0
	s_nop 0
	s_nop 0
	s_nop 0
	s_nop 0
	s_nop 0
	s_nop 0
	s_nop 0
	s_nop 0
	s_nop 0
	s_nop 0
	s_nop 0
	s_nop 0
	s_nop 0
	s_nop 0
	s_nop 0
	s_nop 0
	s_nop 0
	s_nop 0
	s_nop 0
	s_nop 0
	s_nop 0
	s_nop 0
	s_nop 0
	s_nop 0
	s_nop 0
	s_nop 0
	s_nop 0
	s_nop 0
	s_nop 0
	s_nop 0
	s_nop 0
	s_nop 0
	s_nop 0
	s_nop 0
	s_nop 0
	s_nop 0
	s_nop 0
	s_nop 0
	s_nop 0
	s_nop 0
	s_nop 0
	s_nop 0
	s_nop 0
	s_nop 0
	s_nop 0
	s_nop 0
	s_nop 0
	s_nop 0
	s_nop 0
	s_nop 0
	s_nop 0
	s_nop 0
	s_nop 0
	s_nop 0
	s_nop 0
	s_nop 0
	s_nop 0
	s_nop 0
	s_nop 0
	s_nop 0
	s_nop 0
	s_nop 0
	s_nop 0
	s_nop 0
	s_nop 0
	s_nop 0
	s_nop 0
	s_nop 0
	s_nop 0
	s_nop 0
	s_nop 0
	s_nop 0
	s_nop 0
	s_nop 0
	s_nop 0
	s_nop 0
	s_nop 0
	s_nop 0
	s_nop 0
	s_nop 0
	s_nop 0
	s_nop 0
	s_nop 0
	s_nop 0
	s_nop 0
	s_nop 0
	s_nop 0
	s_nop 0
	s_nop 0
	s_nop 0
	s_nop 0
	s_nop 0
	s_nop 0
	s_nop 0
	s_nop 0
	s_nop 0
	s_nop 0
	s_nop 0
	s_nop 0
	s_nop 0
	s_nop 0
	s_nop 0
	s_nop 0
	s_nop 0
	s_nop 0
	s_nop 0
	s_nop 0
	s_nop 0
	s_nop 0
	s_nop 0
	s_nop 0
	s_nop 0
	s_nop 0
	s_nop 0
	s_nop 0
	s_nop 0
	s_nop 0
	s_nop 0
	s_nop 0
	s_nop 0
	s_nop 0
	s_nop 0
	s_nop 0
	s_nop 0
	s_nop 0
	s_nop 0
	s_nop 0
	s_nop 0
	s_nop 0
	s_nop 0
	s_nop 0
	s_nop 0
	s_nop 0
	s_nop 0
	s_nop 0
	s_nop 0
	s_nop 0
	s_nop 0
	s_nop 0
	s_nop 0
	s_nop 0
	s_nop 0
	s_nop 0
	s_nop 0
	s_nop 0
	s_nop 0
	s_nop 0
	s_nop 0
	s_nop 0
	s_nop 0
	s_nop 0
	s_nop 0
	s_nop 0
	s_nop 0
	s_nop 0
	s_nop 0
	s_nop 0
	s_nop 0
	s_nop 0
	s_nop 0
	s_nop 0
	s_nop 0
	s_nop 0
	s_nop 0
	s_nop 0
	s_nop 0
	s_nop 0
	s_nop 0
	s_nop 0
	s_nop 0
	s_nop 0
	s_nop 0
	s_nop 0
	s_nop 0
	s_nop 0
	s_nop 0
	s_nop 0
	s_nop 0
	s_nop 0
	s_nop 0
	s_nop 0
	s_nop 0
	s_nop 0
	s_nop 0
	s_nop 0
	s_nop 0
	s_nop 0
	s_nop 0
	s_nop 0
	s_nop 0
	s_nop 0
	s_nop 0
	s_nop 0
	s_nop 0
	s_nop 0
	s_nop 0
	s_nop 0
	s_nop 0
	s_nop 0
	s_nop 0
	s_nop 0
	s_nop 0
	s_nop 0
	s_nop 0
	s_nop 0
	s_nop 0
	s_nop 0
	s_nop 0
	s_nop 0
	s_nop 0
	s_nop 0
	s_nop 0
	s_nop 0
	s_nop 0
	s_nop 0
	s_nop 0
	s_nop 0
	s_nop 0
	s_nop 0
	s_nop 0
	s_nop 0
	s_nop 0
	s_nop 0
	s_nop 0
	s_nop 0
	s_nop 0
	s_nop 0
	s_nop 0
	s_nop 0
	s_nop 0
	s_nop 0
	s_nop 0
	s_nop 0
	s_nop 0
	s_nop 0
	s_nop 0
	s_nop 0
	s_nop 0
	s_nop 0
	s_nop 0
.LBB0_27:
	s_mov_b64 s[12:13], 0
	s_mov_b64 s[16:17], 0
	s_cbranch_execnz .LBB0_95

; template <int NKS, bool ALLIN = false> ...
;     constexpr int KSTR = NKS * 32 + 16, VSTR = ALLIN ? 288 : 320, KBUF = 64 * KSTR, VBUF = 64 * VSTR, NKB = ALLIN ? 4 : 2;
;     int tid_ = tid_in; asm volatile("" : "+v"(tid_)); const int tid = tid_, lane = tid & 63, wid = __builtin_amdgcn_readfirstlane(tid >> 6), r = lane & 31, hh = lane >> 5;
;     bf16x8 qf[NKS];
; #pragma unroll
;     for (int ks = 0; ks < NKS; ++ks) {
;         if (ks < 8) qf[ks] = *(const bf16x8*)(qn + (size_t)(wid * 32 + r) * ldqn + ks * 16 + hh * 8);
;         else qf[ks] = *(const bf16x8*)(qpe + (size_t)(wid * 32 + r) * ldqpe + (ks - 8) * 16 + hh * 8);
;     }
;     const int key0 = tid >> 4, ch0 = tid & 15;
;     const int keyp = tid >> 3, chp = tid & 7;
;     u32x4 rk0, rk1, rkp, rv0, rv1;
;     ...
;     if constexpr (ALLIN) {
;         u32x4 ak0[4], ak1[4], av0[4], av1[4];
; #pragma unroll
;         for (int t = 0; t < 4; ++t) { ATT_LOAD(t); ak0[t] = rk0; ak1[t] = rk1; av0[t] = rv0; av1[t] = rv1; }
; __global__ void __launch_bounds__(512, 2) mk_fwd(Args a_) {
;     ...
;             for (int ui = bid; ui < 256; ui += G) {
;                 const int b = ui >> 6, hc = (ui >> 4) & 3, qb = ui & 15;
;                 const size_t row0 = (size_t)b * SEQL + qb * 256, kr0 = (size_t)b * 256;
;                 attn_unit<8, true>(lds, tid, qc + row0 * 512 + hc * 128, 512, nullptr, 0, kc + kr0 * 512 + hc * 128, 512, nullptr, 0, vc + kr0 * 512 + hc * 128, 512, oc + row0 * 512 + hc * 128, 512, 4, 4,
.LBB0_30:
	s_and_b64 vcc, exec, s[14:15]
	s_cbranch_vccz .LBB0_94
	s_cmp_gt_i32 s91, 8
	s_mov_b64 s[14:15], -1
	s_cbranch_scc0 .LBB0_40
	s_cmp_eq_u32 s91, 9
	s_mov_b64 s[12:13], -1
	s_cbranch_scc0 .LBB0_39
	s_cmpk_gt_i32 s34, 0xff
	s_mov_b32 s9, s39
	s_mov_b32 s8, s58
	s_cbranch_scc1 .LBB0_38
	v_mbcnt_lo_u32_b32 v0, -1, s9
	v_mbcnt_hi_u32_b32 v0, -1, v0
	v_lshl_add_u32 v164, s8, 6, v0
	s_add_u32 s8, s66, 0x100000
	s_addc_u32 s9, s67, 0
	s_add_u32 s16, s66, 0x200000
	s_addc_u32 s17, s67, 0
	s_mov_b32 s18, s34
	s_cmp_lg_u32 s56, 0x100
	s_cbranch_scc1 .Lp9map_skip
	s_and_b32 s20, s34, 7
	s_lshl_b32 s20, s20, 5
	s_bfe_u32 s21, s34, 0x10003
	s_lshl_b32 s21, s21, 4
	s_or_b32 s20, s20, s21
	s_lshr_b32 s21, s34, 4
	s_or_b32 s18, s20, s21
.Lp9map_skip:
.LBB0_35:
	s_ashr_i32 s20, s18, 6
	s_ashr_i32 s21, s20, 31
	s_lshl_b32 s12, s18, 17
	s_and_b32 s14, s12, 0x1e0000
	s_lshl_b64 s[12:13], s[20:21], 21
	s_or_b32 s12, s12, s14
	s_lshl_b64 s[12:13], s[12:13], 1
	v_readlane_b32 s14, v254, 7
	v_readlane_b32 s15, v254, 8
	s_add_u32 s14, s14, s12
	s_addc_u32 s15, s15, s13
	s_lshl_b32 s19, s18, 3
	s_and_b32 s19, s19, 0x180
	s_lshl_b32 s24, s19, 1
	s_add_u32 s14, s14, s24
	s_addc_u32 s15, s15, 0
	s_lshl_b64 s[20:21], s[20:21], 18
	s_add_u32 s22, s8, s20
	s_addc_u32 s23, s9, s21
	s_add_u32 s22, s22, s24
	s_addc_u32 s23, s23, 0
	s_add_u32 s20, s16, s20
	v_mov_b32_e32 v72, v164
	s_addc_u32 s21, s17, s21
	s_add_u32 s20, s20, s24
	v_ashrrev_i32_e32 v66, 4, v72
	v_lshlrev_b32_e32 v0, 4, v72
	v_ashrrev_i32_e32 v67, 31, v66
	v_and_b32_e32 v68, 0xf0, v0
	v_mov_b32_e32 v69, v1
	s_addc_u32 s21, s21, 0
	v_lshl_add_u64 v[2:3], s[22:23], 0, v[68:69]
	v_lshlrev_b64 v[12:13], 10, v[66:67]
	v_lshl_add_u64 v[10:11], s[20:21], 0, v[68:69]
	v_lshl_add_u64 v[50:51], v[2:3], 0, v[12:13]
	s_mov_b32 s20, 0x8000
	v_add_co_u32_e32 v6, vcc, s20, v50
	v_lshl_add_u64 v[62:63], v[10:11], 0, v[12:13]
	s_nop 0
	v_addc_co_u32_e32 v7, vcc, 0, v51, vcc
	v_add_co_u32_e32 v14, vcc, s20, v62
	s_mov_b32 s20, 0x10000
	s_nop 0
	v_addc_co_u32_e32 v15, vcc, 0, v63, vcc
	s_waitcnt vmcnt(4)
	v_add_co_u32_e32 v18, vcc, s20, v50
	s_mov_b32 s21, 0x18000
	s_nop 0
	v_addc_co_u32_e32 v19, vcc, 0, v51, vcc
	v_add_co_u32_e32 v22, vcc, s21, v50
	global_load_dwordx4 v[2:5], v[50:51], off
	s_nop 0
	global_load_dwordx4 v[6:9], v[6:7], off
	v_addc_co_u32_e32 v23, vcc, 0, v51, vcc
	v_add_co_u32_e32 v26, vcc, s20, v62
	s_mov_b32 s20, 0x28000
	s_nop 0
	v_addc_co_u32_e32 v27, vcc, 0, v63, vcc
	v_add_co_u32_e32 v30, vcc, s21, v62
	s_mov_b32 s21, 0x38000
	s_nop 0
	v_addc_co_u32_e32 v31, vcc, 0, v63, vcc
	v_add_co_u32_e32 v34, vcc, s71, v50
	global_load_dwordx4 v[10:13], v[62:63], off
	s_nop 0
	global_load_dwordx4 v[14:17], v[14:15], off
	v_addc_co_u32_e32 v35, vcc, 0, v51, vcc
	v_add_co_u32_e32 v38, vcc, s20, v50
	global_load_dwordx4 v[18:21], v[18:19], off
	s_nop 0
	global_load_dwordx4 v[22:25], v[22:23], off
	v_addc_co_u32_e32 v39, vcc, 0, v51, vcc
	v_add_co_u32_e32 v42, vcc, s71, v62
	v_bfe_u32 v69, v72, 5, 1
	s_nop 0
	v_addc_co_u32_e32 v43, vcc, 0, v63, vcc
	v_add_co_u32_e32 v46, vcc, s20, v62
	s_mov_b32 s20, 0x30000
	s_nop 0
	v_addc_co_u32_e32 v47, vcc, 0, v63, vcc
	v_add_co_u32_e32 v52, vcc, s20, v50
	global_load_dwordx4 v[26:29], v[26:27], off
	s_nop 0
	global_load_dwordx4 v[30:33], v[30:31], off
	v_addc_co_u32_e32 v53, vcc, 0, v51, vcc
	v_add_co_u32_e32 v54, vcc, s21, v50
	global_load_dwordx4 v[34:37], v[34:35], off
	s_nop 0
	global_load_dwordx4 v[38:41], v[38:39], off
	v_addc_co_u32_e32 v55, vcc, 0, v51, vcc
	v_add_co_u32_e32 v58, vcc, s20, v62
	v_readfirstlane_b32 s20, v72
	s_ashr_i32 s20, s20, 1
	v_addc_co_u32_e32 v59, vcc, 0, v63, vcc
	v_mov_b32_e32 v0, s20
	v_bfi_b32 v70, s70, v0, v72
	v_ashrrev_i32_e32 v71, 31, v70
	v_lshlrev_b64 v[162:163], 10, v[70:71]
	v_add_co_u32_e32 v62, vcc, s21, v62
	v_lshl_add_u64 v[70:71], s[14:15], 0, v[162:163]
	v_lshlrev_b32_e32 v0, 4, v69
	v_addc_co_u32_e32 v63, vcc, 0, v63, vcc
	v_lshl_add_u64 v[70:71], v[70:71], 0, v[0:1]
	global_load_dwordx4 v[42:45], v[42:43], off
	s_nop 0
	global_load_dwordx4 v[46:49], v[46:47], off
	s_nop 0
	global_load_dwordx4 v[50:53], v[52:53], off
	s_nop 0
	global_load_dwordx4 v[54:57], v[54:55], off
	s_movk_i32 s15, 0x120
	global_load_dwordx4 v[58:61], v[58:59], off
	v_readlane_b32 s20, v253, 29
	global_load_dwordx4 v[62:65], v[62:63], off
	s_nop 0
	global_load_dwordx4 v[98:101], v[70:71], off
	global_load_dwordx4 v[102:105], v[70:71], off offset:32
	global_load_dwordx4 v[106:109], v[70:71], off offset:64
	global_load_dwordx4 v[110:113], v[70:71], off offset:96
	global_load_dwordx4 v[114:117], v[70:71], off offset:128
	global_load_dwordx4 v[118:121], v[70:71], off offset:160
	global_load_dwordx4 v[122:125], v[70:71], off offset:192
	global_load_dwordx4 v[126:129], v[70:71], off offset:224
	v_mul_lo_u32 v70, v66, s72
	v_mul_lo_u32 v66, v66, s15
	v_add3_u32 v70, 0, v70, v68
	v_add_u32_e32 v71, 0x2400, v66
	s_waitcnt vmcnt(23)
; template <int NKS, bool ALLIN = false> ...
;     ...
;     if constexpr (ALLIN) {
;         u32x4 ak0[4], ak1[4], av0[4], av1[4];
; #pragma unroll
;         for (int t = 0; t < 4; ++t) { ATT_LOAD(t); ak0[t] = rk0; ak1[t] = rk1; av0[t] = rv0; av1[t] = rv1; }
; #pragma unroll
;         for (int t = 0; t < 4; ++t) { rk0 = ak0[t]; rk1 = ak1[t]; rv0 = av0[t]; rv1 = av1[t]; ATT_STORE(t); }
;     } else { ATT_LOAD(0); ATT_STORE(0); }
;     __syncthreads();
;     f32x16 o[4];
; #pragma unroll
;     for (int d = 0; d < 4; ++d)
; #pragma unroll
;         for (int i = 0; i < 16; ++i) o[d][i] = 0.f;
;     float mrun = -INFINITY, lrun = 0.f;
;     const int g4 = lane >> 4, i16 = lane & 15, q4 = i16 >> 2, p4 = i16 & 3;
;     const int vlane = (4 * hh + q4) * VSTR + (16 * (g4 & 1) + 4 * p4) * 2;
	ds_write_b128 v70, v[2:5]
	s_waitcnt vmcnt(22)
	ds_write_b128 v70, v[6:9] offset:8704
	v_add3_u32 v2, s20, v66, v68
	v_and_b32_e32 v4, 64, v220
	v_xor_b32_e32 v3, 32, v220
	v_add_u32_e32 v4, 64, v4
	v_cmp_lt_i32_e32 vcc, v3, v4
	v_lshlrev_b32_e32 v165, 2, v69
	v_and_b32_e32 v67, 31, v72
	v_cndmask_b32_e32 v3, v220, v3, vcc
	v_lshlrev_b32_e32 v166, 2, v3
	v_lshlrev_b32_e32 v3, 1, v72
	v_and_b32_e32 v3, 32, v3
	v_mov_b32_e32 v76, 0
	s_mov_b32 s14, 4
	s_waitcnt vmcnt(21)
	ds_write_b128 v2, v[10:13]
	v_add3_u32 v2, s20, v71, v68
	v_readlane_b32 s20, v253, 30
	s_waitcnt vmcnt(20)
	ds_write_b128 v2, v[14:17]
	s_waitcnt vmcnt(19)
	ds_write_b128 v70, v[18:21] offset:17408
	s_waitcnt vmcnt(18)
	ds_write_b128 v70, v[22:25] offset:26112
	v_add3_u32 v2, s20, v66, v68
	v_mad_u32_u24 v168, v67, s72, v0
	v_mov_b32_e32 v0, 0xff800000
	v_mov_b32_e32 v18, 0
	v_mov_b32_e32 v19, v76
	v_mov_b32_e32 v20, v76
	v_mov_b32_e32 v21, v76
	v_mov_b32_e32 v22, v76
	v_mov_b32_e32 v23, v76
	v_mov_b32_e32 v24, v76
	v_mov_b32_e32 v25, v76
	v_mov_b32_e32 v4, v76
	v_mov_b32_e32 v5, v76
	s_waitcnt vmcnt(17)
	ds_write_b128 v2, v[26:29]
	v_add3_u32 v2, s20, v71, v68
	v_readlane_b32 s20, v253, 31
	s_waitcnt vmcnt(16)
	ds_write_b128 v2, v[30:33]
	s_waitcnt vmcnt(15)
	ds_write_b128 v70, v[34:37] offset:34816
	s_waitcnt vmcnt(14)
	ds_write_b128 v70, v[38:41] offset:43520
	v_add3_u32 v2, s20, v66, v68
	v_mov_b32_e32 v34, 0
	v_mov_b32_e32 v35, v76
	v_mov_b32_e32 v36, v76
	v_mov_b32_e32 v37, v76
	v_mov_b32_e32 v38, v76
	v_mov_b32_e32 v39, v76
	v_mov_b32_e32 v40, v76
	v_mov_b32_e32 v41, v76
	v_mov_b32_e32 v26, v76
	v_mov_b32_e32 v27, v76
	v_mov_b32_e32 v28, v76
	v_mov_b32_e32 v29, v76
	v_mov_b32_e32 v30, v76
	v_mov_b32_e32 v31, v76
	v_mov_b32_e32 v32, v76
	v_mov_b32_e32 v33, v76
	v_mov_b32_e32 v6, v76
	s_waitcnt vmcnt(13)
	ds_write_b128 v2, v[42:45]
	v_add3_u32 v2, s20, v71, v68
	v_readlane_b32 s20, v253, 32
	s_waitcnt vmcnt(12)
	ds_write_b128 v2, v[46:49]
	s_waitcnt vmcnt(11)
	ds_write_b128 v70, v[50:53] offset:52224
	s_waitcnt vmcnt(10)
	ds_write_b128 v70, v[54:57] offset:60928
	v_add3_u32 v2, s20, v66, v68
	s_waitcnt vmcnt(9)
	ds_write_b128 v2, v[58:61]
	v_add3_u32 v2, s20, v71, v68
	s_waitcnt vmcnt(8)
	ds_write_b128 v2, v[62:65]
	v_lshrrev_b32_e32 v2, 2, v72
	v_and_or_b32 v2, v2, 3, v165
	v_mad_u32_u24 v2, v2, s15, v3
	v_and_b32_e32 v3, 3, v72
	v_lshl_or_b32 v167, v3, 3, v2
	v_mov_b32_e32 v50, 0
	v_mov_b32_e32 v51, v76
	v_mov_b32_e32 v52, v76
	v_mov_b32_e32 v53, v76
	v_mov_b32_e32 v54, v76
	v_mov_b32_e32 v55, v76
	v_mov_b32_e32 v56, v76
	v_mov_b32_e32 v57, v76
	v_mov_b32_e32 v58, v76
	v_mov_b32_e32 v59, v76
	v_mov_b32_e32 v60, v76
	v_mov_b32_e32 v61, v76
	v_mov_b32_e32 v62, v76
	v_mov_b32_e32 v63, v76
	v_mov_b32_e32 v64, v76
	v_mov_b32_e32 v65, v76
	v_mov_b32_e32 v42, v76
	v_mov_b32_e32 v43, v76
	v_mov_b32_e32 v44, v76
	v_mov_b32_e32 v45, v76
	v_mov_b32_e32 v46, v76
	v_mov_b32_e32 v47, v76
	v_mov_b32_e32 v48, v76
	v_mov_b32_e32 v49, v76
	v_mov_b32_e32 v2, 0
	v_mov_b32_e32 v3, v76
	v_mov_b32_e32 v7, v76
	v_mov_b32_e32 v8, v76
	v_mov_b32_e32 v9, v76
	v_mov_b32_e32 v10, v76
	v_mov_b32_e32 v11, v76
	v_mov_b32_e32 v12, v76
	v_mov_b32_e32 v13, v76
	v_mov_b32_e32 v14, v76
	v_mov_b32_e32 v15, v76
	v_mov_b32_e32 v16, v76
	v_mov_b32_e32 v17, v76
	s_waitcnt lgkmcnt(0)
	s_barrier
